# DIL unit: previous-group lse loaded right after V-image DMA issue (merge step waits vmcnt(8) instead of a fresh round trip)
# speedup vs baseline: 1.0104x; 1.0104x over previous
; #define LAS __attribute__((address_space(3)))
; __device__ __forceinline__ void glds16(const void* gsrc, LAS unsigned char* dst_uniform) { __builtin_amdgcn_global_load_lds((const unsigned*)gsrc, (LAS unsigned*)dst_uniform, 16, 0, 0); }
; #define ATT_SYNC() do { asm volatile("s_waitcnt vmcnt(0) lgkmcnt(0)" ::: "memory"); __syncthreads(); } while (0)
; __device__ __forceinline__ void dil_unit(LAS unsigned char* lds, const LAS float* btab, const bf16_t* QKV, int gi, int ldil, int b, int h, int r, int ub, bf16_t* AO, float* lseacc, const int tid) {
;     ...
;     for (int t = 0; t < 5; ++t) { f32x16 acc = {}; const lds_cptr kp = (lds_cptr)lds + (32 * wid + 32 * t + r32) * 256;
; #pragma unroll
;         for (int s = 0; s < 8; ++s) { const bf16x8 kf = *(const LAS bf16x8*)(kp + (((2 * s + hi) ^ r15) << 4)); acc = __builtin_amdgcn_mfma_f32_32x32x16_bf16(kf, qf[s], acc, 0, 0, 0); }
;         S[t] = acc; }
;     ATT_SYNC();
; #pragma unroll 1
;     for (int ii = 0; ii < 12; ++ii) { const int i = wid * 12 + ii, d0 = i / 24, ks = i % 24, kk = 16 * ks + 8 * hi + ((lane >> 2) & 7), cc = lane & 3; int ki = k0 + kk; ki = ki < 0 ? 0 : (ki >= sub_len ? sub_len - 1 : ki);
;         glds16(base + (tokb + ((size_t)ki << ldil)) * 3072 + 2048 + 32 * d0 + 8 * cc, lds + i * 1024); }
;     float m = -3.0e38f;
; #pragma unroll
;     for (int t = 0; t < 5; ++t)
; #pragma unroll
;         for (int rr = 0; rr < 16; ++rr) { const int cr = (rr & 3) + 8 * (rr >> 2) + 4 * hi, jk = 32 * t + cr - r32, ki = k0 + 32 * wid + 32 * t + cr;
;             float s = S[t][rr] + btab[jk + 32];
;             s = ((unsigned)ki < (unsigned)sub_len) ? s : -1e30f;
;             S[t][rr] = s; m = fmaxf(m, s); }
.LBB0_665:
	s_mul_i32 s30, s20, 12
	s_add_i32 s30, s30, s29
	s_mul_hi_i32 s31, s30, 0x2aaaaaab
	s_lshr_b32 s35, s31, 31
	s_ashr_i32 s31, s31, 2
	s_add_i32 s35, s31, s35
	s_mul_i32 s31, s35, 24
	s_sub_i32 s30, s30, s31
	v_lshl_add_u32 v65, s30, 4, v64
	v_min_i32_e32 v66, s18, v65
	v_cmp_lt_i32_e32 vcc, -1, v65
	v_mov_b64_e32 v[68:69], s[2:3]
	v_lshlrev_b32_e32 v208, 1, v212
	v_cndmask_b32_e32 v66, 0, v66, vcc
	v_ashrrev_i32_e32 v67, 31, v66
	v_lshlrev_b64 v[66:67], s12, v[66:67]
	v_lshl_add_u64 v[66:67], v[66:67], 0, s[0:1]
	v_mad_u64_u32 v[68:69], s[30:31], v66, s36, v[68:69]
	v_mov_b32_e32 v66, v69
	v_mad_u64_u32 v[66:67], s[30:31], v67, s36, v[66:67]
	s_lshl_b32 s30, s35, 5
	v_mov_b32_e32 v69, v66
	s_ashr_i32 s31, s30, 31
	v_lshl_add_u64 v[66:67], s[30:31], 1, v[68:69]
	v_lshl_add_u64 v[66:67], v[66:67], 0, v[208:209]
	s_mov_b64 s[30:31], 0x1000
	v_lshl_add_u64 v[66:67], v[66:67], 0, s[30:31]
	s_mov_b32 m0, s26
	s_add_i32 s29, s29, 1
	global_load_lds_dwordx4 v[66:67], off
	s_addk_i32 s26, 0x400
	s_cmp_eq_u32 s29, 12
	s_cbranch_scc0 .LBB0_665
	v_lshlrev_b64 v[242:243], 5, v[218:219]
	s_lshl_b32 s96, s21, 2
	v_lshl_add_u64 v[242:243], s[8:9], 0, v[242:243]
	s_nop 0
	v_lshl_add_u64 v[242:243], v[242:243], 0, s[96:97]
	s_nop 0
	global_load_dword v241, v[242:243], off
	v_mfma_f32_32x32x16_bf16 v[64:79], v[48:51], v[0:3], 0
	s_add_i32 s0, 0, 0x20000
	s_add_i32 s1, s28, s27
	s_mov_b32 s2, 0xff61b1e6
	s_lshl_b32 s96, s24, 1
	v_mfma_f32_32x32x16_bf16 v[64:79], v[24:27], v[80:83], v[64:79]
	v_mfma_f32_32x32x16_bf16 v[64:79], v[52:55], v[84:87], v[64:79]
	v_mfma_f32_32x32x16_bf16 v[64:79], v[32:35], v[88:91], v[64:79]
	v_mfma_f32_32x32x16_bf16 v[64:79], v[56:59], v[92:95], v[64:79]
	v_mfma_f32_32x32x16_bf16 v[64:79], v[36:39], v[96:99], v[64:79]
	v_mfma_f32_32x32x16_bf16 v[64:79], v[60:63], v[100:103], v[64:79]
	v_mfma_f32_32x32x16_bf16 v[48:63], v[44:47], v[0:3], 0
	v_mfma_f32_32x32x16_bf16 v[48:63], v[4:7], v[80:83], v[48:63]
	v_mfma_f32_32x32x16_bf16 v[48:63], v[128:131], v[84:87], v[48:63]
	v_mfma_f32_32x32x16_bf16 v[48:63], v[8:11], v[88:91], v[48:63]
	v_mfma_f32_32x32x16_bf16 v[48:63], v[136:139], v[92:95], v[48:63]
	v_mfma_f32_32x32x16_bf16 v[64:79], v[40:43], v[104:107], v[64:79]
	v_mfma_f32_32x32x16_bf16 v[48:63], v[12:15], v[96:99], v[48:63]
	v_mfma_f32_32x32x16_bf16 v[32:47], v[20:23], v[0:3], 0
	v_mfma_f32_32x32x16_bf16 v[48:63], v[144:147], v[100:103], v[48:63]
	v_mfma_f32_32x32x16_bf16 v[32:47], v[148:151], v[80:83], v[32:47]
	v_mfma_f32_32x32x16_bf16 v[48:63], v[16:19], v[104:107], v[48:63]
	v_mfma_f32_32x32x16_bf16 v[32:47], v[28:31], v[84:87], v[32:47]
	v_mfma_f32_32x32x16_bf16 v[16:31], v[192:195], v[0:3], 0
	v_mfma_f32_32x32x16_bf16 v[0:15], v[140:143], v[0:3], 0
	v_mfma_f32_32x32x16_bf16 v[16:31], v[116:119], v[80:83], v[16:31]
	v_mfma_f32_32x32x16_bf16 v[0:15], v[152:155], v[80:83], v[0:15]
	v_lshlrev_b32_e32 v80, 2, v240
	v_add_u32_e32 v83, s0, v220
	v_lshlrev_b32_e32 v82, 2, v239
	v_mfma_f32_32x32x16_bf16 v[16:31], v[196:199], v[84:87], v[16:31]
	v_mfma_f32_32x32x16_bf16 v[0:15], v[156:159], v[84:87], v[0:15]
	v_or_b32_e32 v84, s1, v82
	v_or_b32_e32 v85, 1, v82
	v_cmp_gt_u32_e32 vcc, s17, v84
	v_or_b32_e32 v86, 2, v82
	v_or_b32_e32 v87, s1, v86
	v_mfma_f32_32x32x16_bf16 v[32:47], v[160:163], v[88:91], v[32:47]
	v_mfma_f32_32x32x16_bf16 v[16:31], v[120:123], v[88:91], v[16:31]
	v_mfma_f32_32x32x16_bf16 v[0:15], v[164:167], v[88:91], v[0:15]
	v_or_b32_e32 v91, 8, v82
	v_or_b32_e32 v90, 16, v82
	v_mfma_f32_32x32x16_bf16 v[32:47], v[108:111], v[92:95], v[32:47]
	v_mfma_f32_32x32x16_bf16 v[16:31], v[200:203], v[92:95], v[16:31]
	v_mfma_f32_32x32x16_bf16 v[0:15], v[172:175], v[92:95], v[0:15]
	v_or_b32_e32 v92, 10, v82
	v_mfma_f32_32x32x16_bf16 v[32:47], v[168:171], v[96:99], v[32:47]
	v_mfma_f32_32x32x16_bf16 v[16:31], v[124:127], v[96:99], v[16:31]
	v_mfma_f32_32x32x16_bf16 v[0:15], v[180:183], v[96:99], v[0:15]
	v_sub_u32_e32 v98, v83, v80
	ds_read2_b32 v[80:81], v98 offset0:32 offset1:33
	ds_read2_b32 v[94:95], v98 offset0:50 offset1:51
	s_waitcnt lgkmcnt(0)
	v_add_f32_e32 v64, v64, v80
	v_or_b32_e32 v80, s1, v85
	v_cndmask_b32_e32 v64, v231, v64, vcc
	v_add_f32_e32 v65, v65, v81
	v_cmp_gt_u32_e32 vcc, s17, v80
	ds_read2_b32 v[80:81], v98 offset0:34 offset1:35
	v_add_f32_e32 v74, v74, v94
	v_cndmask_b32_e32 v65, v231, v65, vcc
	v_cmp_gt_u32_e32 vcc, s17, v87
	v_or_b32_e32 v87, 3, v82
	s_waitcnt lgkmcnt(0)
	v_add_f32_e32 v66, v66, v80
	v_or_b32_e32 v80, s1, v87
	v_cndmask_b32_e32 v66, v231, v66, vcc
	v_add_f32_e32 v67, v67, v81
	v_cmp_gt_u32_e32 vcc, s17, v80
	ds_read2_b32 v[80:81], v98 offset0:40 offset1:41
	v_max3_f32 v84, v64, s2, v65
	v_cndmask_b32_e32 v67, v231, v67, vcc
	v_max3_f32 v88, v84, v66, v67
	v_or_b32_e32 v84, s1, v91
	v_cmp_gt_u32_e32 vcc, s17, v84
	v_or_b32_e32 v84, 9, v82
	s_waitcnt lgkmcnt(0)
	v_add_f32_e32 v68, v68, v80
	v_or_b32_e32 v80, s1, v84
	v_cndmask_b32_e32 v68, v231, v68, vcc
	v_add_f32_e32 v69, v69, v81
	v_cmp_gt_u32_e32 vcc, s17, v80
	v_or_b32_e32 v81, s1, v92
	v_add_f32_e32 v75, v75, v95
	v_cndmask_b32_e32 v69, v231, v69, vcc
	v_max3_f32 v80, v88, v68, v69
	ds_read2_b32 v[88:89], v98 offset0:42 offset1:43
	v_cmp_gt_u32_e32 vcc, s17, v81
	v_or_b32_e32 v81, 11, v82
	v_or_b32_e32 v94, 24, v82
	v_or_b32_e32 v95, 25, v82
	s_waitcnt lgkmcnt(0)
	v_add_f32_e32 v70, v70, v88
	v_or_b32_e32 v88, s1, v81
	v_cndmask_b32_e32 v70, v231, v70, vcc
	v_add_f32_e32 v71, v71, v89
	v_cmp_gt_u32_e32 vcc, s17, v88
	ds_read2_b32 v[88:89], v98 offset0:48 offset1:49
	v_mfma_f32_32x32x16_bf16 v[32:47], v[112:115], v[100:103], v[32:47]
	v_cndmask_b32_e32 v71, v231, v71, vcc
	v_max3_f32 v93, v80, v70, v71
	v_or_b32_e32 v80, s1, v90
	s_waitcnt lgkmcnt(0)
; #define LAS __attribute__((address_space(3)))
; __device__ __forceinline__ void glds16(const void* gsrc, LAS unsigned char* dst_uniform) { __builtin_amdgcn_global_load_lds((const unsigned*)gsrc, (LAS unsigned*)dst_uniform, 16, 0, 0); }
; #define ATT_SYNC() do { asm volatile("s_waitcnt vmcnt(0) lgkmcnt(0)" ::: "memory"); __syncthreads(); } while (0)
; __device__ __forceinline__ void dil_unit(LAS unsigned char* lds, const LAS float* btab, const bf16_t* QKV, int gi, int ldil, int b, int h, int r, int ub, bf16_t* AO, float* lseacc, const int tid) {
;     ...
;     for (int t = 0; t < 5; ++t) { f32x16 acc = {}; const lds_cptr kp = (lds_cptr)lds + (32 * wid + 32 * t + r32) * 256;
; #pragma unroll
;         for (int s = 0; s < 8; ++s) { const bf16x8 kf = *(const LAS bf16x8*)(kp + (((2 * s + hi) ^ r15) << 4)); acc = __builtin_amdgcn_mfma_f32_32x32x16_bf16(kf, qf[s], acc, 0, 0, 0); }
;         S[t] = acc; }
;     ATT_SYNC();
; #pragma unroll 1
;     for (int ii = 0; ii < 12; ++ii) { const int i = wid * 12 + ii, d0 = i / 24, ks = i % 24, kk = 16 * ks + 8 * hi + ((lane >> 2) & 7), cc = lane & 3; int ki = k0 + kk; ki = ki < 0 ? 0 : (ki >= sub_len ? sub_len - 1 : ki);
;         glds16(base + (tokb + ((size_t)ki << ldil)) * 3072 + 2048 + 32 * d0 + 8 * cc, lds + i * 1024); }
;     float m = -3.0e38f;
; #pragma unroll
;     for (int t = 0; t < 5; ++t)
; #pragma unroll
;         for (int rr = 0; rr < 16; ++rr) { const int cr = (rr & 3) + 8 * (rr >> 2) + 4 * hi, jk = 32 * t + cr - r32, ki = k0 + 32 * wid + 32 * t + cr;
;             float s = S[t][rr] + btab[jk + 32];
;             s = ((unsigned)ki < (unsigned)sub_len) ? s : -1e30f;
;             S[t][rr] = s; m = fmaxf(m, s); }
	v_add_f32_e32 v72, v72, v88
	v_cmp_gt_u32_e32 vcc, s17, v80
	v_or_b32_e32 v88, 17, v82
	v_add_f32_e32 v73, v73, v89
	v_cndmask_b32_e32 v80, v231, v72, vcc
	v_or_b32_e32 v72, s1, v88
	v_cmp_gt_u32_e32 vcc, s17, v72
	v_or_b32_e32 v89, 18, v82
	v_mfma_f32_32x32x16_bf16 v[16:31], v[204:207], v[100:103], v[16:31]
	v_cndmask_b32_e32 v72, v231, v73, vcc
	v_max3_f32 v96, v93, v80, v72
	v_or_b32_e32 v73, s1, v89
	v_or_b32_e32 v93, 19, v82
	v_cmp_gt_u32_e32 vcc, s17, v73
	v_or_b32_e32 v73, s1, v93
	s_add_i32 s2, s1, 32
	v_cndmask_b32_e32 v74, v231, v74, vcc
	v_cmp_gt_u32_e32 vcc, s17, v73
	v_mfma_f32_32x32x16_bf16 v[0:15], v[184:187], v[100:103], v[0:15]
	s_nop 0
	v_cndmask_b32_e32 v73, v231, v75, vcc
	v_max3_f32 v99, v96, v74, v73
	ds_read2_b32 v[96:97], v98 offset0:56 offset1:57
	v_or_b32_e32 v75, s1, v94
	v_cmp_gt_u32_e32 vcc, s17, v75
	v_or_b32_e32 v75, s1, v95
	v_mfma_f32_32x32x16_bf16 v[32:47], v[176:179], v[104:107], v[32:47]
	s_waitcnt lgkmcnt(0)
	v_add_f32_e32 v76, v76, v96
	v_cndmask_b32_e32 v76, v231, v76, vcc
	v_add_f32_e32 v77, v77, v97
	v_cmp_gt_u32_e32 vcc, s17, v75
	v_or_b32_e32 v96, 26, v82
	v_or_b32_e32 v97, 27, v82
	v_cndmask_b32_e32 v75, v231, v77, vcc
	v_max3_f32 v100, v99, v76, v75
	ds_read2_b32 v[98:99], v98 offset0:58 offset1:59
	v_or_b32_e32 v77, s1, v96
	v_cmp_gt_u32_e32 vcc, s17, v77
	v_mfma_f32_32x32x16_bf16 v[16:31], v[132:135], v[104:107], v[16:31]
	s_waitcnt lgkmcnt(0)
	v_add_f32_e32 v78, v78, v98
	v_sub_u32_e32 v98, 32, v240
	v_lshlrev_b32_e32 v101, 2, v98
	v_add_u32_e32 v98, v83, v101
	v_add_f32_e32 v79, v79, v99
	ds_read2_b32 v[98:99], v98 offset0:32 offset1:33
	v_cndmask_b32_e32 v77, v231, v78, vcc
	v_or_b32_e32 v78, s1, v97
	v_cmp_gt_u32_e32 vcc, s17, v78
	v_add3_u32 v102, s0, v101, v220
	s_waitcnt lgkmcnt(0)
	v_add_f32_e32 v48, v48, v98
	v_cndmask_b32_e32 v78, v231, v79, vcc
	v_max3_f32 v79, v100, v77, v78
	v_or_b32_e32 v100, s2, v82
	v_cmp_gt_u32_e32 vcc, s17, v100
	v_or_b32_e32 v98, s2, v85
	v_add_f32_e32 v49, v49, v99
	v_cndmask_b32_e32 v48, v231, v48, vcc
	v_cmp_gt_u32_e32 vcc, s17, v98
	ds_read2_b32 v[98:99], v102 offset0:34 offset1:35
	v_mfma_f32_32x32x16_bf16 v[0:15], v[188:191], v[104:107], v[0:15]
	v_cndmask_b32_e32 v49, v231, v49, vcc
	v_max3_f32 v100, v79, v48, v49
	v_or_b32_e32 v79, s2, v86
	s_waitcnt lgkmcnt(0)
	v_add_f32_e32 v50, v50, v98
	v_add_f32_e32 v51, v51, v99
	ds_read2_b32 v[98:99], v102 offset0:40 offset1:41
	v_cmp_gt_u32_e32 vcc, s17, v79
	s_waitcnt lgkmcnt(0)
	v_add_f32_e32 v52, v52, v98
	v_cndmask_b32_e32 v79, v231, v50, vcc
	v_or_b32_e32 v50, s2, v87
	v_cmp_gt_u32_e32 vcc, s17, v50
	v_add_f32_e32 v53, v53, v99
	ds_read2_b32 v[98:99], v102 offset0:42 offset1:43
	v_cndmask_b32_e32 v50, v231, v51, vcc
	v_or_b32_e32 v51, s2, v91
	v_cmp_gt_u32_e32 vcc, s17, v51
	v_or_b32_e32 v51, s2, v84
	v_max3_f32 v100, v100, v79, v50
	v_cndmask_b32_e32 v52, v231, v52, vcc
	v_cmp_gt_u32_e32 vcc, s17, v51
	s_nop 1
	v_cndmask_b32_e32 v51, v231, v53, vcc
	v_max3_f32 v53, v100, v52, v51
	v_or_b32_e32 v100, s2, v92
	v_cmp_gt_u32_e32 vcc, s17, v100
	ds_read2_b32 v[100:101], v102 offset0:48 offset1:49
	s_waitcnt lgkmcnt(0)
	v_add_f32_e32 v54, v54, v98
	v_cndmask_b32_e32 v98, v231, v54, vcc
	v_or_b32_e32 v54, s2, v81
	v_cmp_gt_u32_e32 vcc, s17, v54
	v_add_f32_e32 v54, v56, v100
	v_add_f32_e32 v56, v57, v101
	ds_read2_b32 v[100:101], v102 offset0:50 offset1:51
	v_add_f32_e32 v55, v55, v99
	v_cndmask_b32_e32 v55, v231, v55, vcc
	v_max3_f32 v99, v53, v98, v55
	v_or_b32_e32 v53, s2, v90
	v_cmp_gt_u32_e32 vcc, s17, v53
	v_or_b32_e32 v53, s2, v88
	s_waitcnt lgkmcnt(0)
	v_add_f32_e32 v57, v58, v100
	v_cndmask_b32_e32 v54, v231, v54, vcc
	v_cmp_gt_u32_e32 vcc, s17, v53
	v_add_f32_e32 v58, v59, v101
	ds_read2_b32 v[100:101], v102 offset0:56 offset1:57
	v_cndmask_b32_e32 v53, v231, v56, vcc
	v_or_b32_e32 v56, s2, v89
	v_cmp_gt_u32_e32 vcc, s17, v56
	v_or_b32_e32 v56, s2, v93
	s_waitcnt lgkmcnt(0)
	v_add_f32_e32 v59, v60, v100
	v_cndmask_b32_e32 v57, v231, v57, vcc
	v_cmp_gt_u32_e32 vcc, s17, v56
	v_add_f32_e32 v60, v61, v101
	v_or_b32_e32 v100, s2, v96
	v_cndmask_b32_e32 v56, v231, v58, vcc
	v_or_b32_e32 v58, s2, v94
	v_cmp_gt_u32_e32 vcc, s17, v58
	v_or_b32_e32 v58, s2, v95
	v_max3_f32 v99, v99, v54, v53
	v_cndmask_b32_e32 v59, v231, v59, vcc
	v_cmp_gt_u32_e32 vcc, s17, v58
	v_max3_f32 v99, v99, v57, v56
	s_nop 0
	v_cndmask_b32_e32 v58, v231, v60, vcc
	ds_read2_b32 v[60:61], v102 offset0:58 offset1:59
	v_cmp_gt_u32_e32 vcc, s17, v100
	v_or_b32_e32 v100, s25, v82
	v_max3_f32 v99, v99, v59, v58
	s_waitcnt lgkmcnt(0)
	v_add_f32_e32 v60, v62, v60
	v_or_b32_e32 v62, s2, v97
	v_cndmask_b32_e32 v60, v231, v60, vcc
	v_cmp_gt_u32_e32 vcc, s17, v62
	v_sub_u32_e32 v62, 64, v240
	v_lshlrev_b32_e32 v101, 2, v62
	v_add_u32_e32 v62, v83, v101
	v_add_f32_e32 v61, v63, v61
	ds_read2_b32 v[62:63], v62 offset0:32 offset1:33
	v_cndmask_b32_e32 v61, v231, v61, vcc
	v_cmp_gt_u32_e32 vcc, s17, v100
	v_add3_u32 v102, s0, v101, v220
	v_or_b32_e32 v100, s25, v86
	s_waitcnt lgkmcnt(0)
	v_add_f32_e32 v32, v32, v62
	v_or_b32_e32 v62, s25, v85
	v_cndmask_b32_e32 v32, v231, v32, vcc
	v_add_f32_e32 v33, v33, v63
	v_cmp_gt_u32_e32 vcc, s17, v62
	ds_read2_b32 v[62:63], v102 offset0:34 offset1:35
	v_max3_f32 v99, v99, v60, v61
	v_cndmask_b32_e32 v33, v231, v33, vcc
	v_cmp_gt_u32_e32 vcc, s17, v100
	ds_read2_b32 v[100:101], v102 offset0:40 offset1:41
	s_waitcnt lgkmcnt(0)
	v_add_f32_e32 v34, v34, v62
	v_cndmask_b32_e32 v62, v231, v34, vcc
	v_or_b32_e32 v34, s25, v87
	v_add_f32_e32 v35, v35, v63
	v_add_f32_e32 v36, v36, v100
	v_add_f32_e32 v37, v37, v101
	ds_read2_b32 v[100:101], v102 offset0:42 offset1:43
	v_cmp_gt_u32_e32 vcc, s17, v34
	v_max3_f32 v99, v99, v32, v33
	s_add_i32 s2, s1, 0x60
	v_cndmask_b32_e32 v34, v231, v35, vcc
	v_or_b32_e32 v35, s25, v91
	v_cmp_gt_u32_e32 vcc, s17, v35
	v_or_b32_e32 v35, s25, v84
	s_waitcnt lgkmcnt(0)
; __device__ __forceinline__ void dil_unit(LAS unsigned char* lds, const LAS float* btab, const bf16_t* QKV, int gi, int ldil, int b, int h, int r, int ub, bf16_t* AO, float* lseacc, const int tid) {
;     ...
;     float m = -3.0e38f;
; #pragma unroll
;     for (int t = 0; t < 5; ++t)
; #pragma unroll
;         for (int rr = 0; rr < 16; ++rr) { const int cr = (rr & 3) + 8 * (rr >> 2) + 4 * hi, jk = 32 * t + cr - r32, ki = k0 + 32 * wid + 32 * t + cr;
;             float s = S[t][rr] + btab[jk + 32];
;             s = ((unsigned)ki < (unsigned)sub_len) ? s : -1e30f;
;             S[t][rr] = s; m = fmaxf(m, s); }
	v_add_f32_e32 v38, v38, v100
	v_cndmask_b32_e32 v36, v231, v36, vcc
	v_cmp_gt_u32_e32 vcc, s17, v35
	v_add_f32_e32 v39, v39, v101
	ds_read2_b32 v[100:101], v102 offset0:48 offset1:49
	v_max3_f32 v63, v99, v62, v34
	v_cndmask_b32_e32 v35, v231, v37, vcc
	v_max3_f32 v37, v63, v36, v35
	v_or_b32_e32 v63, s25, v92
	v_cmp_gt_u32_e32 vcc, s17, v63
	s_addk_i32 s1, 0x80
	s_nop 0
	v_cndmask_b32_e32 v63, v231, v38, vcc
	v_or_b32_e32 v38, s25, v81
	v_cmp_gt_u32_e32 vcc, s17, v38
	s_waitcnt lgkmcnt(0)
	v_add_f32_e32 v38, v40, v100
	v_add_f32_e32 v40, v41, v101
	ds_read2_b32 v[100:101], v102 offset0:50 offset1:51
	v_cndmask_b32_e32 v39, v231, v39, vcc
	v_max3_f32 v99, v37, v63, v39
	v_or_b32_e32 v37, s25, v90
	v_cmp_gt_u32_e32 vcc, s17, v37
	s_waitcnt lgkmcnt(0)
	v_add_f32_e32 v41, v42, v100
	v_add_f32_e32 v42, v43, v101
	ds_read2_b32 v[100:101], v102 offset0:56 offset1:57
	v_or_b32_e32 v37, s25, v88
	v_cndmask_b32_e32 v38, v231, v38, vcc
	v_cmp_gt_u32_e32 vcc, s17, v37
	s_waitcnt lgkmcnt(0)
	v_add_f32_e32 v43, v44, v100
	v_cndmask_b32_e32 v37, v231, v40, vcc
	v_or_b32_e32 v40, s25, v89
	v_cmp_gt_u32_e32 vcc, s17, v40
	v_or_b32_e32 v40, s25, v93
	v_add_f32_e32 v44, v45, v101
	v_cndmask_b32_e32 v41, v231, v41, vcc
	v_cmp_gt_u32_e32 vcc, s17, v40
	ds_read2_b32 v[100:101], v102 offset0:58 offset1:59
	v_max3_f32 v99, v99, v38, v37
	v_cndmask_b32_e32 v40, v231, v42, vcc
	v_or_b32_e32 v42, s25, v94
	v_cmp_gt_u32_e32 vcc, s17, v42
	v_or_b32_e32 v42, s25, v95
	s_waitcnt lgkmcnt(0)
	v_add_f32_e32 v45, v46, v100
	v_cndmask_b32_e32 v43, v231, v43, vcc
	v_cmp_gt_u32_e32 vcc, s17, v42
	v_add_f32_e32 v46, v47, v101
	v_or_b32_e32 v100, s2, v82
	v_cndmask_b32_e32 v42, v231, v44, vcc
	v_or_b32_e32 v44, s25, v96
	v_cmp_gt_u32_e32 vcc, s17, v44
	v_or_b32_e32 v44, s25, v97
	v_max3_f32 v99, v99, v41, v40
	v_cndmask_b32_e32 v45, v231, v45, vcc
	v_cmp_gt_u32_e32 vcc, s17, v44
	v_max3_f32 v99, v99, v43, v42
	v_or_b32_e32 v82, s1, v82
	v_cndmask_b32_e32 v44, v231, v46, vcc
	v_sub_u32_e32 v46, 0x60, v240
	v_lshlrev_b32_e32 v101, 2, v46
	v_add_u32_e32 v46, v83, v101
	ds_read2_b32 v[46:47], v46 offset0:32 offset1:33
	v_cmp_gt_u32_e32 vcc, s17, v100
	v_add3_u32 v102, s0, v101, v220
	v_or_b32_e32 v100, s2, v86
	v_max3_f32 v99, v99, v45, v44
	s_waitcnt lgkmcnt(0)
	v_add_f32_e32 v16, v16, v46
	v_or_b32_e32 v46, s2, v85
	v_cndmask_b32_e32 v16, v231, v16, vcc
	v_add_f32_e32 v17, v17, v47
	v_cmp_gt_u32_e32 vcc, s17, v46
	ds_read2_b32 v[46:47], v102 offset0:34 offset1:35
	s_nop 0
	v_cndmask_b32_e32 v17, v231, v17, vcc
	v_cmp_gt_u32_e32 vcc, s17, v100
	ds_read2_b32 v[100:101], v102 offset0:40 offset1:41
	s_waitcnt lgkmcnt(0)
	v_add_f32_e32 v18, v18, v46
	v_cndmask_b32_e32 v46, v231, v18, vcc
	v_or_b32_e32 v18, s2, v87
	v_add_f32_e32 v19, v19, v47
	v_add_f32_e32 v20, v20, v100
	v_add_f32_e32 v21, v21, v101
	ds_read2_b32 v[100:101], v102 offset0:42 offset1:43
	v_cmp_gt_u32_e32 vcc, s17, v18
	v_max3_f32 v99, v99, v16, v17
	s_waitcnt lgkmcnt(0)
	v_add_f32_e32 v22, v22, v100
	v_cndmask_b32_e32 v18, v231, v19, vcc
	v_or_b32_e32 v19, s2, v91
	v_cmp_gt_u32_e32 vcc, s17, v19
	v_or_b32_e32 v19, s2, v84
	v_add_f32_e32 v23, v23, v101
	v_cndmask_b32_e32 v20, v231, v20, vcc
	v_cmp_gt_u32_e32 vcc, s17, v19
	ds_read2_b32 v[100:101], v102 offset0:48 offset1:49
	v_max3_f32 v47, v99, v46, v18
	v_cndmask_b32_e32 v19, v231, v21, vcc
	v_max3_f32 v21, v47, v20, v19
	v_or_b32_e32 v47, s2, v92
	v_cmp_gt_u32_e32 vcc, s17, v47
	s_nop 1
	v_cndmask_b32_e32 v47, v231, v22, vcc
	v_or_b32_e32 v22, s2, v81
	v_cmp_gt_u32_e32 vcc, s17, v22
	s_waitcnt lgkmcnt(0)
	v_add_f32_e32 v22, v24, v100
	v_add_f32_e32 v24, v25, v101
	ds_read2_b32 v[100:101], v102 offset0:50 offset1:51
	v_cndmask_b32_e32 v23, v231, v23, vcc
	v_max3_f32 v99, v21, v47, v23
	v_or_b32_e32 v21, s2, v90
	v_cmp_gt_u32_e32 vcc, s17, v21
	s_waitcnt lgkmcnt(0)
	v_add_f32_e32 v25, v26, v100
	v_add_f32_e32 v26, v27, v101
	ds_read2_b32 v[100:101], v102 offset0:56 offset1:57
	v_or_b32_e32 v21, s2, v88
	v_cndmask_b32_e32 v22, v231, v22, vcc
	v_cmp_gt_u32_e32 vcc, s17, v21
	s_waitcnt lgkmcnt(0)
	v_add_f32_e32 v27, v28, v100
	v_cndmask_b32_e32 v21, v231, v24, vcc
	v_or_b32_e32 v24, s2, v89
	v_cmp_gt_u32_e32 vcc, s17, v24
	v_or_b32_e32 v24, s2, v93
	v_add_f32_e32 v28, v29, v101
	v_cndmask_b32_e32 v25, v231, v25, vcc
	v_cmp_gt_u32_e32 vcc, s17, v24
	ds_read2_b32 v[100:101], v102 offset0:58 offset1:59
	v_max3_f32 v99, v99, v22, v21
	v_cndmask_b32_e32 v24, v231, v26, vcc
	v_or_b32_e32 v26, s2, v94
	v_cmp_gt_u32_e32 vcc, s17, v26
	v_or_b32_e32 v26, s2, v95
	s_waitcnt lgkmcnt(0)
	v_add_f32_e32 v29, v30, v100
	v_cndmask_b32_e32 v27, v231, v27, vcc
	v_cmp_gt_u32_e32 vcc, s17, v26
	v_add_f32_e32 v30, v31, v101
	v_max3_f32 v99, v99, v25, v24
	v_cndmask_b32_e32 v26, v231, v28, vcc
	v_or_b32_e32 v28, s2, v96
	v_cmp_gt_u32_e32 vcc, s17, v28
	v_or_b32_e32 v28, s2, v97
	v_max3_f32 v99, v99, v27, v26
	v_cndmask_b32_e32 v29, v231, v29, vcc
	v_cmp_gt_u32_e32 vcc, s17, v28
	s_nop 1
	v_cndmask_b32_e32 v28, v231, v30, vcc
	v_sub_u32_e32 v30, 0x80, v240
	v_lshlrev_b32_e32 v100, 2, v30
	v_add_u32_e32 v30, v83, v100
	ds_read2_b32 v[30:31], v30 offset0:32 offset1:33
	v_cmp_gt_u32_e32 vcc, s17, v82
	v_add3_u32 v100, s0, v100, v220
	v_or_b32_e32 v83, s1, v86
	v_max3_f32 v99, v99, v29, v28
	s_waitcnt lgkmcnt(0)
	v_add_f32_e32 v0, v0, v30
	v_or_b32_e32 v30, s1, v85
	v_cndmask_b32_e32 v0, v231, v0, vcc
	v_add_f32_e32 v1, v1, v31
	v_cmp_gt_u32_e32 vcc, s17, v30
	ds_read2_b32 v[30:31], v100 offset0:34 offset1:35
	s_waitcnt lgkmcnt(0)
; __device__ __forceinline__ float shx(float v, int lane, int mask) { return __builtin_bit_cast(float, __builtin_amdgcn_ds_bpermute((lane ^ mask) << 2, __builtin_bit_cast(int, v))); }
; __device__ __forceinline__ void dil_unit(LAS unsigned char* lds, const LAS float* btab, const bf16_t* QKV, int gi, int ldil, int b, int h, int r, int ub, bf16_t* AO, float* lseacc, const int tid) {
;     ...
;         for (int rr = 0; rr < 16; ++rr) { const int cr = (rr & 3) + 8 * (rr >> 2) + 4 * hi, jk = 32 * t + cr - r32, ki = k0 + 32 * wid + 32 * t + cr;
;             float s = S[t][rr] + btab[jk + 32];
;             s = ((unsigned)ki < (unsigned)sub_len) ? s : -1e30f;
;             S[t][rr] = s; m = fmaxf(m, s); }
;     m = fmaxf(m, pg8::shx(m, lane, 32));
;     float l = 0.f;
; #pragma unroll
;     for (int t = 0; t < 5; ++t)
; #pragma unroll
;         for (int rr = 0; rr < 16; ++rr) { const float p = __builtin_amdgcn_exp2f(S[t][rr] - m); S[t][rr] = p; l += p; }
	v_add_f32_e32 v2, v2, v30
	v_cndmask_b32_e32 v1, v231, v1, vcc
	v_cmp_gt_u32_e32 vcc, s17, v83
	v_add_f32_e32 v3, v3, v31
	v_max3_f32 v82, v99, v0, v1
	v_cndmask_b32_e32 v30, v231, v2, vcc
	v_or_b32_e32 v2, s1, v87
	v_cmp_gt_u32_e32 vcc, s17, v2
	s_nop 1
	v_cndmask_b32_e32 v2, v231, v3, vcc
	v_max3_f32 v31, v82, v30, v2
	ds_read2_b32 v[82:83], v100 offset0:40 offset1:41
	v_or_b32_e32 v3, s1, v91
	v_cmp_gt_u32_e32 vcc, s17, v3
	v_or_b32_e32 v3, s1, v84
	ds_read2_b32 v[84:85], v100 offset0:48 offset1:49
	s_waitcnt lgkmcnt(0)
	v_add_f32_e32 v4, v4, v82
	v_add_f32_e32 v5, v5, v83
	ds_read2_b32 v[82:83], v100 offset0:42 offset1:43
	v_cndmask_b32_e32 v4, v231, v4, vcc
	v_cmp_gt_u32_e32 vcc, s17, v3
	s_waitcnt lgkmcnt(0)
	v_add_f32_e32 v6, v6, v82
	v_cndmask_b32_e32 v3, v231, v5, vcc
	v_max3_f32 v5, v31, v4, v3
	v_or_b32_e32 v31, s1, v92
	v_cmp_gt_u32_e32 vcc, s17, v31
	v_add_f32_e32 v7, v7, v83
	s_nop 0
	v_cndmask_b32_e32 v82, v231, v6, vcc
	v_or_b32_e32 v6, s1, v81
	v_cmp_gt_u32_e32 vcc, s17, v6
	v_or_b32_e32 v6, s1, v90
	v_or_b32_e32 v81, s1, v96
	v_cndmask_b32_e32 v31, v231, v7, vcc
	v_add_f32_e32 v7, v8, v84
	v_add_f32_e32 v8, v9, v85
	ds_read2_b32 v[84:85], v100 offset0:50 offset1:51
	v_cmp_gt_u32_e32 vcc, s17, v6
	v_or_b32_e32 v6, s1, v88
	v_max3_f32 v5, v5, v82, v31
	v_cndmask_b32_e32 v7, v231, v7, vcc
	v_cmp_gt_u32_e32 vcc, s17, v6
	s_waitcnt lgkmcnt(0)
	v_add_f32_e32 v9, v10, v84
	v_add_f32_e32 v10, v11, v85
	ds_read2_b32 v[84:85], v100 offset0:56 offset1:57
	v_cndmask_b32_e32 v6, v231, v8, vcc
	v_or_b32_e32 v8, s1, v89
	v_cmp_gt_u32_e32 vcc, s17, v8
	v_or_b32_e32 v8, s1, v93
	s_waitcnt lgkmcnt(0)
	v_add_f32_e32 v11, v12, v84
	v_cndmask_b32_e32 v9, v231, v9, vcc
	v_cmp_gt_u32_e32 vcc, s17, v8
	v_add_f32_e32 v12, v13, v85
	v_max3_f32 v5, v5, v7, v6
	v_cndmask_b32_e32 v8, v231, v10, vcc
	v_or_b32_e32 v10, s1, v94
	v_cmp_gt_u32_e32 vcc, s17, v10
	v_or_b32_e32 v10, s1, v95
	v_max3_f32 v5, v5, v9, v8
	v_cndmask_b32_e32 v11, v231, v11, vcc
	v_cmp_gt_u32_e32 vcc, s17, v10
	s_nop 1
	v_cndmask_b32_e32 v10, v231, v12, vcc
	ds_read2_b32 v[12:13], v100 offset0:58 offset1:59
	v_cmp_gt_u32_e32 vcc, s17, v81
	v_max3_f32 v5, v5, v11, v10
	s_waitcnt lgkmcnt(0)
	v_add_f32_e32 v12, v14, v12
	v_cndmask_b32_e32 v81, v231, v12, vcc
	v_or_b32_e32 v12, s1, v97
	v_add_f32_e32 v13, v15, v13
	v_cmp_gt_u32_e32 vcc, s17, v12
	v_lshlrev_b32_e32 v12, 2, v238
	v_xor_b32_e32 v12, 0x80, v12
	v_cndmask_b32_e32 v15, v231, v13, vcc
	v_max3_f32 v5, v5, v81, v15
	ds_bpermute_b32 v13, v12, v5
	s_and_b64 vcc, exec, s[10:11]
	s_waitcnt lgkmcnt(0)
	v_max_f32_e32 v13, v13, v13
	v_max_f32_e32 v5, v5, v13
	v_sub_f32_e32 v13, v64, v5
	v_exp_f32_e32 v13, v13
	v_sub_f32_e32 v14, v65, v5
	v_exp_f32_e32 v14, v14
	v_sub_f32_e32 v73, v73, v5
	v_add_f32_e32 v64, 0, v13
	v_exp_f32_e32 v73, v73
	v_add_f32_e32 v65, v14, v64
	v_sub_f32_e32 v64, v66, v5
	v_exp_f32_e32 v64, v64
	v_sub_f32_e32 v75, v75, v5
	v_exp_f32_e32 v75, v75
	v_sub_f32_e32 v48, v48, v5
	v_add_f32_e32 v66, v64, v65
	v_sub_f32_e32 v65, v67, v5
	v_exp_f32_e32 v65, v65
	v_exp_f32_e32 v48, v48
	v_sub_f32_e32 v49, v49, v5
	v_exp_f32_e32 v49, v49
	v_add_f32_e32 v67, v65, v66
	v_sub_f32_e32 v66, v68, v5
	v_exp_f32_e32 v66, v66
	v_sub_f32_e32 v50, v50, v5
	v_exp_f32_e32 v50, v50
	v_sub_f32_e32 v52, v52, v5
	v_add_f32_e32 v68, v66, v67
	v_sub_f32_e32 v67, v69, v5
	v_exp_f32_e32 v67, v67
	v_sub_f32_e32 v51, v51, v5
	v_exp_f32_e32 v51, v51
	v_sub_f32_e32 v55, v55, v5
	v_add_f32_e32 v69, v67, v68
	v_sub_f32_e32 v68, v70, v5
	v_exp_f32_e32 v68, v68
	v_exp_f32_e32 v55, v55
	v_sub_f32_e32 v54, v54, v5
	v_exp_f32_e32 v83, v54
	v_add_f32_e32 v70, v68, v69
	v_sub_f32_e32 v69, v71, v5
	v_exp_f32_e32 v69, v69
	v_sub_f32_e32 v53, v53, v5
	v_exp_f32_e32 v84, v53
	v_sub_f32_e32 v53, v57, v5
	v_add_f32_e32 v71, v69, v70
	v_sub_f32_e32 v70, v80, v5
	v_exp_f32_e32 v70, v70
	v_exp_f32_e32 v85, v53
	v_sub_f32_e32 v53, v56, v5
	v_exp_f32_e32 v86, v53
	v_add_f32_e32 v80, v70, v71
	v_sub_f32_e32 v71, v72, v5
	v_exp_f32_e32 v71, v71
	v_sub_f32_e32 v72, v74, v5
	v_exp_f32_e32 v72, v72
	v_sub_f32_e32 v53, v59, v5
	v_add_f32_e32 v80, v71, v80
	v_exp_f32_e32 v87, v53
	v_add_f32_e32 v74, v72, v80
	v_add_f32_e32 v80, v73, v74
	v_sub_f32_e32 v74, v76, v5
	v_exp_f32_e32 v74, v74
	v_sub_f32_e32 v53, v58, v5
	v_exp_f32_e32 v88, v53
	v_sub_f32_e32 v53, v60, v5
	v_add_f32_e32 v76, v74, v80
	v_add_f32_e32 v80, v75, v76
	v_sub_f32_e32 v76, v77, v5
	v_exp_f32_e32 v76, v76
	v_sub_f32_e32 v77, v78, v5
	v_exp_f32_e32 v77, v77
	v_exp_f32_e32 v89, v53
	v_add_f32_e32 v80, v76, v80
	v_sub_f32_e32 v53, v61, v5
	v_add_f32_e32 v78, v77, v80
	v_add_f32_e32 v78, v48, v78
	v_add_f32_e32 v80, v49, v78
	v_sub_f32_e32 v78, v79, v5
	v_exp_f32_e32 v78, v78
	v_exp_f32_e32 v90, v53
	v_sub_f32_e32 v32, v32, v5
	v_exp_f32_e32 v32, v32
	v_add_f32_e32 v79, v78, v80
	v_add_f32_e32 v80, v50, v79
	v_exp_f32_e32 v79, v52
	v_sub_f32_e32 v33, v33, v5
	v_exp_f32_e32 v33, v33
	v_sub_f32_e32 v53, v62, v5
	v_add_f32_e32 v52, v79, v80
	v_sub_f32_e32 v80, v98, v5
	v_exp_f32_e32 v80, v80
	v_add_f32_e32 v52, v51, v52
	v_exp_f32_e32 v91, v53
	v_sub_f32_e32 v34, v34, v5
	v_add_f32_e32 v52, v80, v52
	v_add_f32_e32 v52, v55, v52
	v_add_f32_e32 v52, v83, v52
	v_add_f32_e32 v52, v84, v52
	v_add_f32_e32 v52, v85, v52
	v_add_f32_e32 v52, v86, v52
	v_add_f32_e32 v52, v87, v52
	v_add_f32_e32 v52, v88, v52
	v_add_f32_e32 v52, v89, v52
	v_add_f32_e32 v52, v90, v52
	v_exp_f32_e32 v34, v34
	v_sub_f32_e32 v36, v36, v5
	v_add_f32_e32 v52, v32, v52
	v_exp_f32_e32 v36, v36
	v_sub_f32_e32 v35, v35, v5
	v_add_f32_e32 v52, v33, v52
	v_exp_f32_e32 v35, v35
	v_sub_f32_e32 v53, v63, v5
	v_add_f32_e32 v52, v91, v52
; __device__ __forceinline__ float shx(float v, int lane, int mask) { return __builtin_bit_cast(float, __builtin_amdgcn_ds_bpermute((lane ^ mask) << 2, __builtin_bit_cast(int, v))); }
; __device__ __forceinline__ void dil_unit(LAS unsigned char* lds, const LAS float* btab, const bf16_t* QKV, int gi, int ldil, int b, int h, int r, int ub, bf16_t* AO, float* lseacc, const int tid) {
;     ...
;     for (int t = 0; t < 5; ++t)
; #pragma unroll
;         for (int rr = 0; rr < 16; ++rr) { const float p = __builtin_amdgcn_exp2f(S[t][rr] - m); S[t][rr] = p; l += p; }
;     l += pg8::shx(l, lane, 32);
;     const float inv = __builtin_amdgcn_rcpf(l), lse = m + __builtin_amdgcn_logf(l);
;     bf16x8 pf[10];
; #pragma unroll
;     for (int t = 0; t < 5; ++t) { pf[2 * t] = pack8(S[t], 0); pf[2 * t + 1] = pack8(S[t], 8); }
;     bf16_t* orow = AO + qtok * 1024 + h * 128;
;     u32x4 oldv[4][2] = {};
;     if (gi > 0) {
; #pragma unroll
;         for (int d0 = 0; d0 < 4; ++d0)
; #pragma unroll
;             for (int g2 = 0; g2 < 2; ++g2) oldv[d0][g2] = *(const u32x4*)(orow + 32 * d0 + 16 * g2 + (hi ? 8 : 0)); }
;     float wa = 0.f, wb = 1.f, ln = lse;
;     float* lp = lseacc + qtok * 8 + h;
;     if (gi > 0) { const float la = *lp, mx = fmaxf(la, lse); ln = mx + __builtin_amdgcn_logf(__builtin_amdgcn_exp2f(la - mx) + __builtin_amdgcn_exp2f(lse - mx)); wa = __builtin_amdgcn_exp2f(la - ln); wb = __builtin_amdgcn_exp2f(lse - ln); }
	v_exp_f32_e32 v92, v53
	v_sub_f32_e32 v39, v39, v5
	v_add_f32_e32 v52, v34, v52
	v_exp_f32_e32 v39, v39
	v_sub_f32_e32 v38, v38, v5
	v_add_f32_e32 v52, v36, v52
	v_exp_f32_e32 v38, v38
	v_sub_f32_e32 v37, v37, v5
	v_add_f32_e32 v52, v35, v52
	v_exp_f32_e32 v37, v37
	v_sub_f32_e32 v41, v41, v5
	v_add_f32_e32 v52, v92, v52
	v_exp_f32_e32 v41, v41
	v_sub_f32_e32 v40, v40, v5
	v_add_f32_e32 v52, v39, v52
	v_exp_f32_e32 v93, v40
	v_sub_f32_e32 v43, v43, v5
	v_add_f32_e32 v52, v38, v52
	v_exp_f32_e32 v43, v43
	v_sub_f32_e32 v42, v42, v5
	v_add_f32_e32 v52, v37, v52
	v_exp_f32_e32 v42, v42
	v_sub_f32_e32 v45, v45, v5
	v_add_f32_e32 v52, v41, v52
	v_exp_f32_e32 v94, v45
	v_sub_f32_e32 v44, v44, v5
	v_add_f32_e32 v40, v93, v52
	v_exp_f32_e32 v95, v44
	v_sub_f32_e32 v16, v16, v5
	v_add_f32_e32 v40, v43, v40
	v_exp_f32_e32 v16, v16
	v_sub_f32_e32 v17, v17, v5
	v_add_f32_e32 v40, v42, v40
	v_exp_f32_e32 v17, v17
	v_sub_f32_e32 v44, v46, v5
	v_add_f32_e32 v40, v94, v40
	v_exp_f32_e32 v96, v44
	v_sub_f32_e32 v18, v18, v5
	v_add_f32_e32 v40, v95, v40
	v_exp_f32_e32 v18, v18
	v_sub_f32_e32 v20, v20, v5
	v_add_f32_e32 v40, v16, v40
	v_exp_f32_e32 v20, v20
	v_sub_f32_e32 v19, v19, v5
	v_add_f32_e32 v40, v17, v40
	v_exp_f32_e32 v19, v19
	v_sub_f32_e32 v44, v47, v5
	v_add_f32_e32 v40, v96, v40
	v_exp_f32_e32 v97, v44
	v_sub_f32_e32 v23, v23, v5
	v_add_f32_e32 v40, v18, v40
	v_exp_f32_e32 v23, v23
	v_sub_f32_e32 v22, v22, v5
	v_add_f32_e32 v40, v20, v40
	v_exp_f32_e32 v22, v22
	v_sub_f32_e32 v21, v21, v5
	v_add_f32_e32 v40, v19, v40
	v_exp_f32_e32 v21, v21
	v_sub_f32_e32 v25, v25, v5
	v_add_f32_e32 v40, v97, v40
	v_exp_f32_e32 v25, v25
	v_sub_f32_e32 v24, v24, v5
	v_add_f32_e32 v40, v23, v40
	v_exp_f32_e32 v24, v24
	v_sub_f32_e32 v27, v27, v5
	v_add_f32_e32 v40, v22, v40
	v_exp_f32_e32 v27, v27
	v_sub_f32_e32 v26, v26, v5
	v_add_f32_e32 v40, v21, v40
	v_exp_f32_e32 v26, v26
	v_sub_f32_e32 v29, v29, v5
	v_add_f32_e32 v40, v25, v40
	v_exp_f32_e32 v29, v29
	v_sub_f32_e32 v28, v28, v5
	v_add_f32_e32 v40, v24, v40
	v_exp_f32_e32 v28, v28
	v_sub_f32_e32 v0, v0, v5
	v_add_f32_e32 v40, v27, v40
	v_exp_f32_e32 v0, v0
	v_sub_f32_e32 v1, v1, v5
	v_add_f32_e32 v40, v26, v40
	v_exp_f32_e32 v1, v1
	v_sub_f32_e32 v30, v30, v5
	v_add_f32_e32 v40, v29, v40
	v_exp_f32_e32 v30, v30
	v_sub_f32_e32 v2, v2, v5
	v_add_f32_e32 v40, v28, v40
	v_exp_f32_e32 v98, v2
	v_sub_f32_e32 v4, v4, v5
	v_add_f32_e32 v40, v0, v40
	v_exp_f32_e32 v4, v4
	v_sub_f32_e32 v3, v3, v5
	v_add_f32_e32 v40, v1, v40
	v_exp_f32_e32 v99, v3
	v_sub_f32_e32 v3, v82, v5
	v_add_f32_e32 v40, v30, v40
	v_exp_f32_e32 v82, v3
	v_sub_f32_e32 v3, v31, v5
	v_add_f32_e32 v2, v98, v40
	v_exp_f32_e32 v31, v3
	v_sub_f32_e32 v3, v7, v5
	v_add_f32_e32 v2, v4, v2
	v_exp_f32_e32 v7, v3
	v_sub_f32_e32 v3, v6, v5
	v_add_f32_e32 v2, v99, v2
	v_exp_f32_e32 v6, v3
	v_sub_f32_e32 v3, v9, v5
	v_add_f32_e32 v2, v82, v2
	v_exp_f32_e32 v9, v3
	v_sub_f32_e32 v3, v8, v5
	v_add_f32_e32 v2, v31, v2
	v_exp_f32_e32 v8, v3
	v_sub_f32_e32 v3, v11, v5
	v_add_f32_e32 v2, v7, v2
	v_exp_f32_e32 v11, v3
	v_sub_f32_e32 v3, v10, v5
	v_add_f32_e32 v2, v6, v2
	v_exp_f32_e32 v10, v3
	v_sub_f32_e32 v3, v81, v5
	v_add_f32_e32 v2, v9, v2
	v_exp_f32_e32 v81, v3
	v_sub_f32_e32 v3, v15, v5
	v_add_f32_e32 v2, v8, v2
	v_exp_f32_e32 v15, v3
	v_add_f32_e32 v2, v11, v2
	v_add_f32_e32 v2, v10, v2
	v_add_f32_e32 v2, v81, v2
	v_add_f32_e32 v2, v15, v2
	ds_bpermute_b32 v3, v12, v2
	v_cvt_pk_bf16_f32 v60, v13, v14
	v_cvt_pk_bf16_f32 v61, v64, v65
	v_cvt_pk_bf16_f32 v62, v66, v67
	v_cvt_pk_bf16_f32 v63, v68, v69
	v_cvt_pk_bf16_f32 v56, v70, v71
	v_cvt_pk_bf16_f32 v57, v72, v73
	v_cvt_pk_bf16_f32 v58, v74, v75
	v_cvt_pk_bf16_f32 v59, v76, v77
	v_cvt_pk_bf16_f32 v52, v48, v49
	v_cvt_pk_bf16_f32 v53, v78, v50
	v_cvt_pk_bf16_f32 v54, v79, v51
	v_cvt_pk_bf16_f32 v55, v80, v55
	v_cvt_pk_bf16_f32 v48, v83, v84
	v_cvt_pk_bf16_f32 v49, v85, v86
	v_cvt_pk_bf16_f32 v50, v87, v88
	v_cvt_pk_bf16_f32 v51, v89, v90
	v_cvt_pk_bf16_f32 v44, v32, v33
	v_cvt_pk_bf16_f32 v45, v91, v34
	v_cvt_pk_bf16_f32 v46, v36, v35
	v_cvt_pk_bf16_f32 v47, v92, v39
	v_cvt_pk_bf16_f32 v40, v38, v37
	v_cvt_pk_bf16_f32 v41, v41, v93
	v_cvt_pk_bf16_f32 v42, v43, v42
	v_cvt_pk_bf16_f32 v43, v94, v95
	v_cvt_pk_bf16_f32 v36, v16, v17
	v_cvt_pk_bf16_f32 v37, v96, v18
	v_cvt_pk_bf16_f32 v38, v20, v19
	v_cvt_pk_bf16_f32 v39, v97, v23
	v_cvt_pk_bf16_f32 v32, v22, v21
	v_cvt_pk_bf16_f32 v33, v25, v24
	v_cvt_pk_bf16_f32 v34, v27, v26
	v_cvt_pk_bf16_f32 v35, v29, v28
	v_cvt_pk_bf16_f32 v28, v0, v1
	v_lshlrev_b64 v[0:1], 11, v[218:219]
	v_lshl_add_u64 v[0:1], s[6:7], 0, v[0:1]
	v_cvt_pk_bf16_f32 v29, v30, v98
	v_cvt_pk_bf16_f32 v30, v4, v99
	v_cvt_pk_bf16_f32 v31, v82, v31
	v_cvt_pk_bf16_f32 v24, v7, v6
	v_cvt_pk_bf16_f32 v25, v9, v8
	v_cvt_pk_bf16_f32 v26, v11, v10
	v_cvt_pk_bf16_f32 v27, v81, v15
	v_lshl_add_u64 v[0:1], v[0:1], 0, s[96:97]
	v_mov_b32_e32 v88, 0
	v_mov_b32_e32 v16, 0
	v_mov_b32_e32 v17, 0
	v_mov_b32_e32 v18, 0
	v_mov_b32_e32 v19, 0
	v_mov_b32_e32 v20, 0
	v_mov_b32_e32 v21, 0
	v_mov_b32_e32 v22, 0
	v_mov_b32_e32 v23, 0
	v_mov_b32_e32 v64, 0
	v_mov_b32_e32 v65, 0
	v_mov_b32_e32 v66, 0
	v_mov_b32_e32 v67, 0
	v_mov_b32_e32 v68, 0
	v_mov_b32_e32 v69, 0
	v_mov_b32_e32 v70, 0
	v_mov_b32_e32 v71, 0
	v_mov_b32_e32 v72, 0
	v_mov_b32_e32 v73, 0
	v_mov_b32_e32 v74, 0
	v_mov_b32_e32 v75, 0
	v_mov_b32_e32 v76, 0
	v_mov_b32_e32 v77, 0
	v_mov_b32_e32 v78, 0
	v_mov_b32_e32 v79, 0
	v_mov_b32_e32 v80, 0
	v_mov_b32_e32 v81, 0
	v_mov_b32_e32 v82, 0
	v_mov_b32_e32 v83, 0
	v_mov_b32_e32 v84, 0
	v_mov_b32_e32 v85, 0
	v_mov_b32_e32 v86, 0
	v_mov_b32_e32 v87, 0
	s_cbranch_vccz .LBB0_668
	v_and_b32_e32 v4, 8, v221
	v_lshlrev_b32_e32 v208, 1, v4
	v_lshl_add_u64 v[6:7], v[0:1], 0, v[208:209]
	global_load_dwordx4 v[84:87], v[6:7], off
	global_load_dwordx4 v[80:83], v[6:7], off offset:32
	global_load_dwordx4 v[76:79], v[6:7], off offset:64
	global_load_dwordx4 v[72:75], v[6:7], off offset:96
	global_load_dwordx4 v[68:71], v[6:7], off offset:128
	global_load_dwordx4 v[64:67], v[6:7], off offset:160
	global_load_dwordx4 v[20:23], v[6:7], off offset:192
	global_load_dwordx4 v[16:19], v[6:7], off offset:224
.LBB0_668:
	s_waitcnt lgkmcnt(0)
	v_add_f32_e32 v2, v2, v3
	v_log_f32_e32 v3, v2
	s_lshl_b32 s96, s21, 2
	s_andn2_b64 vcc, exec, s[10:11]
	v_add_f32_e32 v94, v5, v3
	v_lshlrev_b64 v[4:5], 5, v[218:219]
	v_lshl_add_u64 v[4:5], s[8:9], 0, v[4:5]
	v_lshl_add_u64 v[90:91], v[4:5], 0, s[96:97]
	s_cbranch_vccnz .LBB0_670
	v_max_f32_e32 v4, v94, v94
	s_waitcnt vmcnt(8)
	v_mov_b32_e32 v3, v241
	v_max_f32_e32 v5, v3, v3
	v_max_f32_e32 v4, v5, v4
	v_sub_f32_e32 v5, v3, v4
	v_sub_f32_e32 v6, v94, v4
	v_exp_f32_e32 v5, v5
	v_exp_f32_e32 v6, v6
	s_nop 0
	v_add_f32_e32 v5, v5, v6
	v_log_f32_e32 v5, v5
	s_nop 0
	v_add_f32_e32 v4, v4, v5
	v_sub_f32_e32 v3, v3, v4
	v_sub_f32_e32 v5, v94, v4
	v_exp_f32_e32 v88, v3
	v_exp_f32_e32 v89, v5
	v_mov_b32_e32 v94, v4
	s_branch .LBB0_671
